# static s_setprio 1 for waves 4-7 during the attention phase, on top of the attention address diets
# baseline (speedup 1.0000x reference)
.LBB0_178:
	s_or_b64 exec, exec, s[6:7]
	s_waitcnt lgkmcnt(0)
	s_barrier
	v_mbcnt_lo_u32_b32 v2, -1, 0
	v_mbcnt_hi_u32_b32 v2, -1, v2
	s_load_dwordx2 s[6:7], s[0:1], 0x98
	s_waitcnt lgkmcnt(0)
	s_load_dwordx2 s[8:9], s[0:1], 16
	s_waitcnt lgkmcnt(0)
	s_load_dwordx2 s[10:11], s[0:1], 24
	s_waitcnt lgkmcnt(0)
	s_load_dwordx2 s[12:13], s[0:1], 32
	s_waitcnt lgkmcnt(0)
	s_load_dwordx2 s[14:15], s[0:1], 40
	s_waitcnt lgkmcnt(0)
	s_nop 0
	v_ashrrev_i32_e32 v3, 31, v2
	v_lshlrev_b64 v[4:5], 2, v[2:3]
	v_lshl_add_u64 v[6:7], s[8:9], 0, v[4:5]
	v_lshl_add_u64 v[8:9], s[10:11], 0, v[4:5]
	global_load_dword v10, v[6:7], off
	global_load_dword v11, v[6:7], off offset:256
	global_load_dword v12, v[8:9], off
	global_load_dword v13, v[8:9], off offset:256
	v_lshl_add_u64 v[6:7], s[12:13], 0, v[4:5]
	v_lshl_add_u64 v[4:5], s[14:15], 0, v[4:5]
	global_load_dword v8, v[6:7], off
	global_load_dword v9, v[6:7], off offset:256
	global_load_dword v14, v[4:5], off
	global_load_dword v15, v[4:5], off offset:256
	s_abs_i32 s13, s24
	v_cvt_f32_u32_e32 v3, s13
	v_lshlrev_b32_e32 v2, 2, v2
	v_xor_b32_e32 v6, 4, v2
	v_xor_b32_e32 v7, 8, v2
	v_xor_b32_e32 v16, 16, v2
	v_xor_b32_e32 v17, 32, v2
	v_xor_b32_e32 v18, 64, v2
	v_xor_b32_e32 v19, 0x80, v2
	v_rcp_iflag_f32_e32 v20, v3
	v_readfirstlane_b32 s10, v0
	s_lshr_b32 s10, s10, 4
	s_and_b32 s10, s10, 0xffffffc
	s_add_i32 s10, s10, 0
	s_mov_b32 s8, 0x3fb8aa3b
	s_add_i32 s29, s10, 0x20c00
	s_sub_i32 s15, 0, s13
	s_sub_i32 s11, s24, s17
	s_add_i32 s14, s11, 0x1ff
	s_sub_i32 s11, 0xfffffe01, s11
	s_xor_b32 s28, s14, s24
	s_max_i32 s14, s14, s11
	s_mov_b32 s9, 0xc2ce8ed0
	s_mov_b32 s12, 0x42b17218
	v_mov_b32_e32 v1, 0x7f800000
	s_ashr_i32 s28, s28, 31
	s_load_dwordx2 s[10:11], s[0:1], 48
	s_waitcnt lgkmcnt(0)
	s_mov_b32 s25, 0
	s_waitcnt vmcnt(4)
	v_pk_mul_f32 v[2:3], v[10:11], v[12:13]
	s_nop 0
	v_add_f32_e32 v2, v2, v3
	s_waitcnt vmcnt(0)
	v_pk_mul_f32 v[4:5], v[8:9], v[14:15]
	s_nop 0
	v_add_f32_e32 v3, v4, v5
	ds_bpermute_b32 v4, v6, v2
	ds_bpermute_b32 v5, v6, v3
	v_mul_f32_e32 v8, 0x4f7ffffe, v20
	v_cvt_u32_f32_e32 v8, v8
	v_mov_b32_e32 v6, s29
	s_waitcnt lgkmcnt(1)
	v_add_f32_e32 v2, v2, v4
	s_waitcnt lgkmcnt(0)
	v_add_f32_e32 v3, v3, v5
	ds_bpermute_b32 v4, v7, v2
	ds_bpermute_b32 v5, v7, v3
	v_readfirstlane_b32 s29, v8
	s_mul_i32 s15, s15, s29
	s_mul_hi_u32 s15, s29, s15
	s_waitcnt lgkmcnt(1)
	v_add_f32_e32 v2, v2, v4
	s_waitcnt lgkmcnt(0)
	v_add_f32_e32 v3, v3, v5
	ds_bpermute_b32 v4, v16, v2
	ds_bpermute_b32 v5, v16, v3
	s_add_i32 s29, s29, s15
	s_mul_hi_u32 s15, s14, s29
	s_mul_i32 s29, s15, s13
	s_waitcnt lgkmcnt(1)
	v_add_f32_e32 v2, v2, v4
	s_waitcnt lgkmcnt(0)
	v_add_f32_e32 v3, v3, v5
	ds_bpermute_b32 v4, v17, v2
	ds_bpermute_b32 v5, v17, v3
	s_sub_i32 s14, s14, s29
	s_add_i32 s30, s15, 1
	s_sub_i32 s29, s14, s13
	s_waitcnt lgkmcnt(1)
	v_add_f32_e32 v2, v2, v4
	s_waitcnt lgkmcnt(0)
	v_add_f32_e32 v3, v3, v5
	ds_bpermute_b32 v4, v18, v2
	ds_bpermute_b32 v5, v18, v3
	s_cmp_ge_u32 s14, s13
	s_cselect_b32 s15, s30, s15
	s_cselect_b32 s14, s29, s14
	s_waitcnt lgkmcnt(1)
	v_add_f32_e32 v2, v2, v4
	s_waitcnt lgkmcnt(0)
	v_add_f32_e32 v3, v3, v5
	ds_bpermute_b32 v4, v19, v2
	ds_bpermute_b32 v5, v19, v3
	s_add_i32 s29, s15, 1
	s_cmp_ge_u32 s14, s13
	s_cselect_b32 s13, s29, s15
	s_waitcnt lgkmcnt(1)
	v_add_f32_e32 v2, v2, v4
	s_waitcnt lgkmcnt(0)
	v_add_f32_e32 v3, v3, v5
	v_mul_f32_e32 v4, 0x3fb8aa3b, v2
	v_mul_f32_e32 v5, 0x3fb8aa3b, v3
	v_fma_f32 v7, v2, s8, -v4
	v_rndne_f32_e32 v8, v4
	v_fma_f32 v9, v3, s8, -v5
	v_rndne_f32_e32 v10, v5
	v_fmac_f32_e32 v7, 0x32a5705f, v2
	v_sub_f32_e32 v4, v4, v8
	v_fmac_f32_e32 v9, 0x32a5705f, v3
	v_sub_f32_e32 v5, v5, v10
	v_add_f32_e32 v4, v4, v7
	v_cvt_i32_f32_e32 v8, v8
	v_add_f32_e32 v5, v5, v9
	v_exp_f32_e32 v4, v4
	v_cvt_i32_f32_e32 v10, v10
	v_exp_f32_e32 v5, v5
	v_cmp_ngt_f32_e32 vcc, s9, v2
	v_ldexp_f32 v4, v4, v8
	s_xor_b32 s8, s13, s28
	v_ldexp_f32 v5, v5, v10
	v_cndmask_b32_e32 v4, 0, v4, vcc
	v_cmp_ngt_f32_e32 vcc, s9, v3
	s_sub_i32 s8, s8, s28
	s_cmp_lt_i32 s8, 1
	v_cndmask_b32_e32 v5, 0, v5, vcc
	v_cmp_nlt_f32_e32 vcc, s12, v2
	s_nop 1
	v_cndmask_b32_e32 v2, v1, v4, vcc
	v_cmp_nlt_f32_e32 vcc, s12, v3
	s_nop 1
	v_cndmask_b32_e32 v1, v1, v5, vcc
	v_sub_f32_e32 v1, v2, v1
	v_add_f32_e32 v1, 0x3e4ccccd, v1
	ds_write_b32 v6, v1
	s_waitcnt lgkmcnt(0)
	s_cbranch_scc1 .LBB0_463
	s_add_u32 s38, s6, 0x16100000
	s_addc_u32 s39, s7, 0
	s_add_u32 s40, s6, 0x3e100000
	s_addc_u32 s41, s7, 0
	s_lshl_b32 s8, s8, 1
	s_max_i32 s42, s8, 1
	s_add_u32 s43, s6, 0x16601100
	s_mov_b32 s14, 0xffd7ff00
	s_mov_b32 s28, 0xffd80000
	s_movk_i32 s30, 0xff00
	s_addc_u32 s44, s7, 0
	s_movk_i32 s45, 0x5000
	s_mov_b64 s[12:13], 0x100
	v_mov_b32_e32 v223, 0
	s_brev_b32 s46, -2
	s_add_i32 s47, 0, 0x18000
	s_mov_b32 s15, -1
	s_mov_b32 s29, -1
	s_movk_i32 s48, 0x70
	s_brev_b32 s49, 1
	s_mov_b32 s50, 0x41000000
	s_movk_i32 s51, 0x100
	s_mov_b32 s31, -1
	s_movk_i32 s52, 0xc000
	v_mov_b32_e32 v1, 0x3727c5ac
	s_mov_b32 s53, 0xf800000
	v_mov_b32_e32 v224, 0x260
	v_mov_b32_e32 v225, 0xff800000
	v_mbcnt_lo_u32_b32 v255, -1, 0
	v_mbcnt_hi_u32_b32 v255, -1, v255
	v_lshrrev_b32_e32 v251, 4, v255
	v_and_b32_e32 v252, 15, v255
	v_xor_b32_e32 v252, v252, v251
	v_lshlrev_b32_e32 v252, 4, v252
	v_mul_u32_u24_e32 v251, 0xa000, v251
	v_add_u32_e32 v251, v251, v252
	s_mul_i32 s98, s19, 0x50000
	v_add_u32_e32 v251, s98, v251
	v_xor_b32_e32 v252, 64, v251
	v_add_u32_e32 v252, 0x28000, v252
	v_bfe_u32 v253, v255, 2, 3
	s_and_b32 s98, s19, 1
	s_lshl_b32 s98, s98, 4
	v_or_b32_e32 v253, s98, v253
	v_mul_u32_u24_e32 v253, 0xa000, v253
	v_lshrrev_b32_e32 v254, 5, v255
	v_lshlrev_b32_e32 v254, 6, v254
	v_add_u32_e32 v253, v253, v254
	v_bfe_u32 v254, v255, 4, 1
	v_xor_b32_e32 v254, v254, v255
	v_and_b32_e32 v254, 3, v254
	v_lshlrev_b32_e32 v254, 4, v254
	v_add_u32_e32 v253, v253, v254
	v_xor_b32_e32 v254, 32, v253
	v_add_u32_e32 v254, 0x50000, v254
	v_lshrrev_b32_e32 v2, 3, v255
	v_ashrrev_i32_e32 v3, 5, v255
	v_and_or_b32 v2, v2, 2, v3
	v_lshlrev_b32_e32 v3, 1, v3
	v_bfe_u32 v5, v255, 1, 1
	v_and_b32_e32 v3, 2, v3
	v_and_b32_e32 v6, 12, v255
	v_or3_b32 v5, v6, v3, v5
	v_lshlrev_b32_e32 v2, 11, v2
	v_lshlrev_b32_e32 v7, 3, v255
	v_and_b32_e32 v7, 8, v7
	v_lshlrev_b32_e32 v5, 4, v5
	v_add3_u32 v255, v7, v2, v5
	s_cmp_lt_u32 s19, 4
	s_cbranch_scc1 .Lattn_prio_skip
	s_setprio 1

.LBB0_463:
	s_setprio 0
	s_waitcnt vmcnt(0)
	s_waitcnt vmcnt(0) lgkmcnt(0)
	s_barrier
	v_mbcnt_lo_u32_b32 v1, -1, 0
	v_mbcnt_hi_u32_b32 v1, -1, v1
	s_load_dwordx2 s[8:9], s[0:1], 0x98
	s_waitcnt lgkmcnt(0)
	s_load_dwordx2 s[6:7], s[0:1], 0x90
	s_waitcnt lgkmcnt(0)
	s_cmpk_gt_i32 s16, 0x7ff
	s_load_dwordx2 s[6:7], s[0:1], 0x90
	s_waitcnt lgkmcnt(0)
	s_load_dwordx2 s[10:11], s[0:1], 56
	s_waitcnt lgkmcnt(0)
	s_cbranch_scc1 .LBB0_471
	s_add_u32 s25, s8, 0x16100000
	s_addc_u32 s34, s9, 0
	v_lshlrev_b32_e32 v26, 3, v1
	s_lshl_b32 s6, s17, 6
	s_lshl_b32 s7, s19, 3
	v_ashrrev_i32_e32 v27, 31, v26
	s_add_i32 s35, s6, s7
	s_lshl_b32 s6, s17, 12
	s_lshl_b32 s7, s19, 9
	v_lshlrev_b64 v[28:29], 1, v[26:27]
	s_lshl_b32 s36, s24, 6
	s_add_i32 s17, s6, s7
	s_lshl_b32 s19, s24, 12
	s_mov_b64 s[12:13], 0x2000
	s_mov_b64 s[14:15], 0x4000
	s_movk_i32 s37, 0x3000
	s_movk_i32 s38, 0x5000
	s_mov_b32 s39, 0x16105000
	s_mov_b32 s40, 0x16104000
	s_mov_b32 s41, 0x3e101000
	s_mov_b32 s42, 0x1610f000
	s_mov_b32 s43, 0x1610e000
	s_mov_b32 s44, 0x3e103000
	s_mov_b32 s45, 0x16119000
	s_mov_b32 s46, 0x16118000
	s_mov_b32 s47, 0x3e105000
	s_mov_b32 s48, 0x16123000
	s_mov_b32 s49, 0x16122000
	s_mov_b32 s50, 0x3e107000
	v_mov_b32_e32 v30, 0
	s_mov_b32 s51, s16
